# FFN-in: next-unit tile index and pointer scalar code moved from the unit boundary into the first MFMA block of the unit
# baseline (speedup 1.0000x reference)
; #define PG8_STAGE(bufoff, gbase, voff) do { _Pragma("unroll") for (int _i = 0; _i < 2; ++_i) \
;         __builtin_amdgcn_global_load_lds((const unsigned*)((const char*)(gbase) + (voff)[_i]), (PG8_LAS unsigned*)(lds + (bufoff) + ldsw + _i * 8192), 16, 0, 0); } while (0)
; #define PG8_LDA(dst, b, h) do { _Pragma("unroll") for (int m = 0; m < 4; ++m) _Pragma("unroll") for (int k = 0; k < 2; ++k) dst[m][k] = *(const PG8_LAS bf16x8*)(lds + PG8_SA(b, h) + aoff + m * 2048 + k * 1024); } while (0)
; #define PG8_LDB(dst, b, h) do { _Pragma("unroll") for (int n = 0; n < 2; ++n) _Pragma("unroll") for (int k = 0; k < 2; ++k) dst[n][k] = *(const PG8_LAS bf16x8*)(lds + PG8_SB(b, h) + boff + n * 2048 + k * 1024); } while (0)
; #define PG8_MMA(ai, bj, At, Bt) do { __builtin_amdgcn_s_setprio(1); _Pragma("unroll") for (int m = 0; m < 4; ++m) _Pragma("unroll") for (int n = 0; n < 2; ++n) _Pragma("unroll") for (int k = 0; k < 2; ++k) \
;         acc[ai][bj][m][n] = __builtin_amdgcn_mfma_f32_16x16x32_bf16(Bt[n][k], At[m][k], acc[ai][bj][m][n], 0, 0, 0); __builtin_amdgcn_s_setprio(0); } while (0)
; #define PG8_WAIT_V(n) asm volatile("s_waitcnt vmcnt(" #n ")" ::: "memory")
; #define PG8_BAR __builtin_amdgcn_s_barrier()
;     __host__ __device__ bool next(int i, Unit& u) const {
;         const long L = (long)i * G + c; if (L >= nwg) return false;
;         int wgid = (int)L; { const int q = nwg / NXCD, r = nwg % NXCD, xcd = wgid % NXCD, off = wgid / NXCD; wgid = (xcd < r ? xcd * (q + 1) : r * (q + 1) + (xcd - r) * q) + off; }
;         const int nig = WGM * nN, gid = wgid / nig, fm = gid * WGM, gsz = (nM - fm) < WGM ? (nM - fm) : WGM;
;         u.pm = fm + ((wgid % nig) % gsz); u.pn = (wgid % nig) / gsz; return true;
;     }
; template <class Epi, class Sched, bool ALIGN_EPI = false, bool SP2 = false>
; __device__ __forceinline__ void gemm_phase(PG8_LAS unsigned char* lds, const Gemm g, const Sched& S, const Epi& E) {
;     ...
;         const bool has_next = S.next(ui + 1, nxt);
;         const char* nA = has_next ? (const char*)g.A + (size_t)nxt.pm * tstep : cA; const char* nB = has_next ? (const char*)g.Bt + (size_t)nxt.pn * tstep : cB;
;     ...
;             PG8_LDB(B0, 0, 0); PG8_LDB(B1, 0, 1); PG8_SCHED; PG8_LDA(At, 0, 0); PG8_STAGE(PG8_SA(1, 1), a1 + hstep, voffA);
;             PG8_WAIT_V(8); PG8_WAIT_L(0); PG8_BAR; PG8_MMA(0, 0, At, B0); PG8_MMA(0, 1, At, B1); PG8_BAR; PG8_SCHED;
.LBB0_195:
.LBB0_197:
	s_add_u32 s6, s6, 0x40080
	s_addc_u32 s7, s7, 0
	s_add_u32 s60, s44, 0x100
	s_addc_u32 s61, s45, 0
	s_mov_b32 s62, -2
	s_cmp_eq_u32 s96, 0
	s_cbranch_scc1 .Lg1_noe2
	s_barrier
	s_mov_b32 s96, 0
.Lg1_noe2:
	s_add_u32 s44, s6, 0xfffc0080
	s_addc_u32 s45, s7, -1
	s_add_i32 s63, 0, 0x10000
	s_cmp_eq_u32 s62, 12
	s_cselect_b32 s51, s22, s45
	s_cselect_b32 s50, s23, s44
	s_cselect_b32 s45, s19, s61
	s_cselect_b32 s44, s39, s60
	s_add_i32 s73, 0, 0x14000
	v_add_u32_e32 v140, s63, v191
	v_add_u32_e32 v168, s73, v191
	ds_read_b128 v[128:131], v140
	ds_read_b128 v[132:135], v140 offset:1024
	ds_read_b128 v[136:139], v140 offset:2048
	ds_read_b128 v[140:143], v140 offset:3072
	ds_read_b128 v[144:147], v168
	ds_read_b128 v[148:151], v168 offset:1024
	ds_read_b128 v[164:167], v168 offset:2048
	ds_read_b128 v[168:171], v168 offset:3072
	v_lshl_add_u64 v[202:203], s[6:7], 0, v[160:161]
	s_add_i32 m0, s52, 0xc000
	ds_read_b128 v[172:175], v193
	ds_read_b128 v[176:179], v193 offset:1024
	ds_read_b128 v[186:189], v193 offset:2048
	ds_read_b128 v[194:197], v193 offset:3072
	ds_read_b128 v[198:201], v193 offset:4096
	ds_read_b128 v[216:219], v193 offset:5120
	ds_read_b128 v[224:227], v193 offset:6144
	ds_read_b128 v[230:233], v193 offset:7168
	global_load_lds_dwordx4 v[202:203], off
	v_lshl_add_u64 v[202:203], s[6:7], 0, v[162:163]
	s_add_i32 m0, s52, 0xe000
	s_nop 0
	global_load_lds_dwordx4 v[202:203], off
	s_waitcnt vmcnt(8)
	s_waitcnt lgkmcnt(0)
	s_setprio 1
	s_barrier
	v_mfma_f32_16x16x32_bf16 v[124:127], v[128:131], v[172:175], 0
	s_add_i32 s58, s58, 1
	s_mul_i32 s4, s58, s81
	v_mfma_f32_16x16x32_bf16 v[112:115], v[136:139], v[172:175], 0
	s_mul_hi_u32 s5, s58, s24
	s_add_i32 s5, s5, s4
	v_mfma_f32_16x16x32_bf16 v[108:111], v[128:131], v[186:189], 0
	s_mul_i32 s4, s58, s24
	v_mfma_f32_16x16x32_bf16 v[96:99], v[136:139], v[186:189], 0
	s_add_u32 s22, s4, s2
	s_addc_u32 s23, s5, s33
	v_mfma_f32_16x16x32_bf16 v[92:95], v[128:131], v[198:201], 0
	v_mov_b64_e32 v[0:1], 0x1600
	v_cmp_lt_i64_e64 s[4:5], s[22:23], v[0:1]
	v_mfma_f32_16x16x32_bf16 v[80:83], v[136:139], v[198:201], 0
	s_ashr_i32 s18, s22, 31
	s_lshr_b32 s18, s18, 29
	v_mfma_f32_16x16x32_bf16 v[76:79], v[128:131], v[224:227], 0
	s_add_i32 s18, s22, s18
	s_ashr_i32 s19, s18, 3
	v_mfma_f32_16x16x32_bf16 v[64:67], v[136:139], v[224:227], 0
	s_and_b32 s18, s18, -8
	s_sub_i32 s18, s22, s18
	v_mfma_f32_16x16x32_bf16 v[124:127], v[132:135], v[176:179], v[124:127]
	s_cmp_lt_i32 s18, 0
	s_movk_i32 s22, 0x2c1
	s_cselect_b32 s22, s22, 0x2c0
	v_mfma_f32_16x16x32_bf16 v[112:115], v[140:143], v[176:179], v[112:115]
	s_mul_i32 s18, s22, s18
	s_add_i32 s18, s18, s19
	v_mfma_f32_16x16x32_bf16 v[108:111], v[132:135], v[194:197], v[108:111]
	s_mul_hi_i32 s19, s18, 0x2e8ba2e9
	s_lshr_b32 s22, s19, 31
	v_mfma_f32_16x16x32_bf16 v[96:99], v[140:143], v[194:197], v[96:99]
	s_ashr_i32 s19, s19, 5
	s_add_i32 s19, s19, s22
	v_mfma_f32_16x16x32_bf16 v[92:95], v[132:135], v[216:219], v[92:95]
	s_lshl_b32 s22, s19, 3
	s_mulk_i32 s19, 0xb0
	v_mfma_f32_16x16x32_bf16 v[80:83], v[140:143], v[216:219], v[80:83]
	s_sub_i32 s19, s18, s19
	s_lshr_b32 s18, s19, 3
	v_mfma_f32_16x16x32_bf16 v[76:79], v[132:135], v[230:233], v[76:79]
	s_and_b32 s19, s19, 7
	s_add_i32 s38, s19, s22
	v_mfma_f32_16x16x32_bf16 v[64:67], v[140:143], v[230:233], v[64:67]
	s_ashr_i32 s39, s38, 31
	s_lshl_b64 s[22:23], s[38:39], 19
	s_setprio 0
	s_setprio 1
	v_mfma_f32_16x16x32_bf16 v[120:123], v[144:147], v[172:175], 0
	s_add_u32 s40, s13, s22
	s_addc_u32 s41, s36, s23
	v_mfma_f32_16x16x32_bf16 v[116:119], v[164:167], v[172:175], 0
	s_and_b64 s[22:23], s[4:5], exec
	s_cselect_b32 s22, s41, s7
	s_cselect_b32 s23, s40, s6
	v_mfma_f32_16x16x32_bf16 v[104:107], v[144:147], v[186:189], 0
	s_ashr_i32 s19, s18, 31
	s_lshl_b64 s[42:43], s[18:19], 19
	v_mfma_f32_16x16x32_bf16 v[100:103], v[164:167], v[186:189], 0
	s_add_u32 s42, s37, s42
	s_addc_u32 s43, s46, s43
	v_mfma_f32_16x16x32_bf16 v[88:91], v[144:147], v[198:201], 0
	s_and_b64 s[76:77], s[4:5], exec
	s_cselect_b32 s19, s43, s45
	s_cselect_b32 s39, s42, s44
	v_mfma_f32_16x16x32_bf16 v[84:87], v[164:167], v[198:201], 0
	v_mfma_f32_16x16x32_bf16 v[72:75], v[144:147], v[224:227], 0
	v_mfma_f32_16x16x32_bf16 v[68:71], v[164:167], v[224:227], 0
	v_mfma_f32_16x16x32_bf16 v[120:123], v[148:151], v[176:179], v[120:123]
	v_mfma_f32_16x16x32_bf16 v[116:119], v[168:171], v[176:179], v[116:119]
	v_mfma_f32_16x16x32_bf16 v[104:107], v[148:151], v[194:197], v[104:107]
	v_mfma_f32_16x16x32_bf16 v[100:103], v[168:171], v[194:197], v[100:103]
	v_mfma_f32_16x16x32_bf16 v[88:91], v[148:151], v[216:219], v[88:91]
	v_mfma_f32_16x16x32_bf16 v[84:87], v[168:171], v[216:219], v[84:87]
	v_mfma_f32_16x16x32_bf16 v[72:75], v[148:151], v[230:233], v[72:75]
	v_mfma_f32_16x16x32_bf16 v[68:71], v[168:171], v[230:233], v[68:71]
	s_barrier
	s_setprio 0
	s_add_i32 s63, s63, s47
	v_lshl_add_u64 v[202:203], s[44:45], 0, v[180:181]
	s_mov_b32 m0, s63
	ds_read_b128 v[172:175], v193 offset:16384
	ds_read_b128 v[176:179], v193 offset:17408
	ds_read_b128 v[186:189], v193 offset:18432
	ds_read_b128 v[194:197], v193 offset:19456
	ds_read_b128 v[198:201], v193 offset:20480
	ds_read_b128 v[216:219], v193 offset:21504
	ds_read_b128 v[224:227], v193 offset:22528
	ds_read_b128 v[230:233], v193 offset:23552
	global_load_lds_dwordx4 v[202:203], off
	s_add_i32 m0, s63, 0x2000
	s_add_u32 s76, s44, 0x40000
	v_lshl_add_u64 v[208:209], s[44:45], 0, v[152:153]
	s_addc_u32 s77, s45, 0
	s_add_i32 s63, s73, s47
	global_load_lds_dwordx4 v[208:209], off
	v_lshl_add_u64 v[220:221], s[76:77], 0, v[180:181]
	s_mov_b32 m0, s63
	v_lshl_add_u64 v[234:235], s[50:51], 0, v[154:155]
	global_load_lds_dwordx4 v[220:221], off
	v_lshl_add_u64 v[220:221], s[76:77], 0, v[152:153]
	s_add_i32 m0, s63, 0x2000
	s_nop 0
	global_load_lds_dwordx4 v[220:221], off
	v_lshl_add_u64 v[220:221], s[50:51], 0, v[156:157]
	s_mov_b32 m0, s52
	s_nop 0
	global_load_lds_dwordx4 v[220:221], off
	s_mov_b32 m0, s53
	s_nop 0
	global_load_lds_dwordx4 v[234:235], off
	s_waitcnt vmcnt(8)
	s_waitcnt lgkmcnt(0)
	s_setprio 1
	s_barrier
; #define PG8_STAGE(bufoff, gbase, voff) do { _Pragma("unroll") for (int _i = 0; _i < 2; ++_i) \
;         __builtin_amdgcn_global_load_lds((const unsigned*)((const char*)(gbase) + (voff)[_i]), (PG8_LAS unsigned*)(lds + (bufoff) + ldsw + _i * 8192), 16, 0, 0); } while (0)
; #define PG8_LDA(dst, b, h) do { _Pragma("unroll") for (int m = 0; m < 4; ++m) _Pragma("unroll") for (int k = 0; k < 2; ++k) dst[m][k] = *(const PG8_LAS bf16x8*)(lds + PG8_SA(b, h) + aoff + m * 2048 + k * 1024); } while (0)
; #define PG8_LDB(dst, b, h) do { _Pragma("unroll") for (int n = 0; n < 2; ++n) _Pragma("unroll") for (int k = 0; k < 2; ++k) dst[n][k] = *(const PG8_LAS bf16x8*)(lds + PG8_SB(b, h) + boff + n * 2048 + k * 1024); } while (0)
; #define PG8_MMA(ai, bj, At, Bt) do { __builtin_amdgcn_s_setprio(1); _Pragma("unroll") for (int m = 0; m < 4; ++m) _Pragma("unroll") for (int n = 0; n < 2; ++n) _Pragma("unroll") for (int k = 0; k < 2; ++k) \
;         acc[ai][bj][m][n] = __builtin_amdgcn_mfma_f32_16x16x32_bf16(Bt[n][k], At[m][k], acc[ai][bj][m][n], 0, 0, 0); __builtin_amdgcn_s_setprio(0); } while (0)
; #define PG8_WAIT_V(n) asm volatile("s_waitcnt vmcnt(" #n ")" ::: "memory")
; #define PG8_WAIT_L(n) asm volatile("s_waitcnt lgkmcnt(" #n ")" ::: "memory")
; #define PG8_BAR __builtin_amdgcn_s_barrier()
; #define PG8_SCHED __builtin_amdgcn_sched_barrier(0)
; template <class Epi, class Sched, bool ALIGN_EPI = false, bool SP2 = false>
; __device__ __forceinline__ void gemm_phase(PG8_LAS unsigned char* lds, const Gemm g, const Sched& S, const Epi& E) {
;     ...
;             PG8_LDB(B0, 0, 0); PG8_LDB(B1, 0, 1); PG8_SCHED; PG8_LDA(At, 0, 0); PG8_STAGE(PG8_SA(1, 1), a1 + hstep, voffA);
;             PG8_WAIT_V(8); PG8_WAIT_L(0); PG8_BAR; PG8_MMA(0, 0, At, B0); PG8_MMA(0, 1, At, B1); PG8_BAR; PG8_SCHED;
;             PG8_LDA(At, 0, 1); PG8_STAGE(PG8_SB(0, 0), b2, voffB); PG8_STAGE(PG8_SB(0, 1), b2 + hstep, voffB); PG8_STAGE(PG8_SA(0, 0), a2, voffA);
;             PG8_WAIT_V(8); PG8_WAIT_L(0); PG8_BAR; PG8_MMA(1, 0, At, B0); PG8_MMA(1, 1, At, B1); PG8_BAR; PG8_SCHED;
;             PG8_LDB(B0, 1, 0); PG8_LDB(B1, 1, 1); PG8_SCHED; PG8_LDA(At, 1, 0); PG8_STAGE(PG8_SA(0, 1), a2 + hstep, voffA);
;             PG8_WAIT_V(8); PG8_WAIT_L(0); PG8_BAR; PG8_MMA(0, 0, At, B0); PG8_MMA(0, 1, At, B1); PG8_BAR; PG8_SCHED;
	v_mfma_f32_16x16x32_bf16 v[60:63], v[128:131], v[172:175], 0
	v_mfma_f32_16x16x32_bf16 v[48:51], v[136:139], v[172:175], 0
	v_mfma_f32_16x16x32_bf16 v[44:47], v[128:131], v[186:189], 0
	v_mfma_f32_16x16x32_bf16 v[32:35], v[136:139], v[186:189], 0
	v_mfma_f32_16x16x32_bf16 v[28:31], v[128:131], v[198:201], 0
	v_mfma_f32_16x16x32_bf16 v[16:19], v[136:139], v[198:201], 0
	v_mfma_f32_16x16x32_bf16 v[12:15], v[128:131], v[224:227], 0
	v_mfma_f32_16x16x32_bf16 v[4:7], v[136:139], v[224:227], 0
	v_mfma_f32_16x16x32_bf16 v[60:63], v[132:135], v[176:179], v[60:63]
	v_mfma_f32_16x16x32_bf16 v[48:51], v[140:143], v[176:179], v[48:51]
	v_mfma_f32_16x16x32_bf16 v[44:47], v[132:135], v[194:197], v[44:47]
	v_mfma_f32_16x16x32_bf16 v[32:35], v[140:143], v[194:197], v[32:35]
	v_mfma_f32_16x16x32_bf16 v[28:31], v[132:135], v[216:219], v[28:31]
	v_mfma_f32_16x16x32_bf16 v[16:19], v[140:143], v[216:219], v[16:19]
	v_mfma_f32_16x16x32_bf16 v[12:15], v[132:135], v[230:233], v[12:15]
	v_mfma_f32_16x16x32_bf16 v[4:7], v[140:143], v[230:233], v[4:7]
	s_setprio 0
	s_setprio 1
	v_mfma_f32_16x16x32_bf16 v[56:59], v[144:147], v[172:175], 0
	v_mfma_f32_16x16x32_bf16 v[52:55], v[164:167], v[172:175], 0
	v_mfma_f32_16x16x32_bf16 v[40:43], v[144:147], v[186:189], 0
	v_mfma_f32_16x16x32_bf16 v[36:39], v[164:167], v[186:189], 0
	v_mfma_f32_16x16x32_bf16 v[24:27], v[144:147], v[198:201], 0
	v_mfma_f32_16x16x32_bf16 v[20:23], v[164:167], v[198:201], 0
	v_mfma_f32_16x16x32_bf16 v[8:11], v[144:147], v[224:227], 0
	v_mfma_f32_16x16x32_bf16 v[0:3], v[164:167], v[224:227], 0
	v_mfma_f32_16x16x32_bf16 v[56:59], v[148:151], v[176:179], v[56:59]
	v_mfma_f32_16x16x32_bf16 v[52:55], v[168:171], v[176:179], v[52:55]
	v_mfma_f32_16x16x32_bf16 v[40:43], v[148:151], v[194:197], v[40:43]
	v_mfma_f32_16x16x32_bf16 v[36:39], v[168:171], v[194:197], v[36:39]
	v_mfma_f32_16x16x32_bf16 v[24:27], v[148:151], v[216:219], v[24:27]
	v_mfma_f32_16x16x32_bf16 v[20:23], v[168:171], v[216:219], v[20:23]
	v_mfma_f32_16x16x32_bf16 v[8:11], v[148:151], v[230:233], v[8:11]
	v_mfma_f32_16x16x32_bf16 v[0:3], v[168:171], v[230:233], v[0:3]
	s_barrier
	s_setprio 0
	s_add_i32 s63, 0, 0x18000
	s_add_i32 s73, 0, 0x1c000
	v_add_u32_e32 v140, s63, v191
	v_add_u32_e32 v168, s73, v191
	ds_read_b128 v[128:131], v140
	ds_read_b128 v[132:135], v140 offset:1024
	ds_read_b128 v[136:139], v140 offset:2048
	ds_read_b128 v[140:143], v140 offset:3072
	ds_read_b128 v[144:147], v168
	ds_read_b128 v[148:151], v168 offset:1024
	ds_read_b128 v[164:167], v168 offset:2048
	ds_read_b128 v[168:171], v168 offset:3072
	s_add_u32 s50, s50, 0x40000
	s_addc_u32 s51, s51, 0
	s_mov_b32 m0, s54
	v_lshl_add_u64 v[236:237], s[50:51], 0, v[156:157]
	ds_read_b128 v[172:175], v193 offset:32768
	ds_read_b128 v[176:179], v193 offset:33792
	ds_read_b128 v[186:189], v193 offset:34816
	ds_read_b128 v[194:197], v193 offset:35840
	ds_read_b128 v[198:201], v193 offset:36864
	ds_read_b128 v[216:219], v193 offset:37888
	ds_read_b128 v[224:227], v193 offset:38912
	ds_read_b128 v[230:233], v193 offset:39936
	global_load_lds_dwordx4 v[236:237], off
	v_lshl_add_u64 v[236:237], s[50:51], 0, v[154:155]
	s_mov_b32 m0, s55
	s_nop 0
	global_load_lds_dwordx4 v[236:237], off
	s_waitcnt vmcnt(8)
	s_waitcnt lgkmcnt(0)
	s_setprio 1
	s_barrier
	v_mfma_f32_16x16x32_bf16 v[124:127], v[128:131], v[172:175], v[124:127]
	v_mfma_f32_16x16x32_bf16 v[112:115], v[136:139], v[172:175], v[112:115]
	v_mfma_f32_16x16x32_bf16 v[108:111], v[128:131], v[186:189], v[108:111]
	v_mfma_f32_16x16x32_bf16 v[96:99], v[136:139], v[186:189], v[96:99]
	v_mfma_f32_16x16x32_bf16 v[92:95], v[128:131], v[198:201], v[92:95]
	v_mfma_f32_16x16x32_bf16 v[80:83], v[136:139], v[198:201], v[80:83]
	v_mfma_f32_16x16x32_bf16 v[76:79], v[128:131], v[224:227], v[76:79]
	v_mfma_f32_16x16x32_bf16 v[64:67], v[136:139], v[224:227], v[64:67]
	v_mfma_f32_16x16x32_bf16 v[124:127], v[132:135], v[176:179], v[124:127]
	v_mfma_f32_16x16x32_bf16 v[112:115], v[140:143], v[176:179], v[112:115]
	v_mfma_f32_16x16x32_bf16 v[108:111], v[132:135], v[194:197], v[108:111]
	v_mfma_f32_16x16x32_bf16 v[96:99], v[140:143], v[194:197], v[96:99]
	v_mfma_f32_16x16x32_bf16 v[92:95], v[132:135], v[216:219], v[92:95]
	v_mfma_f32_16x16x32_bf16 v[80:83], v[140:143], v[216:219], v[80:83]
	v_mfma_f32_16x16x32_bf16 v[76:79], v[132:135], v[230:233], v[76:79]
	v_mfma_f32_16x16x32_bf16 v[64:67], v[140:143], v[230:233], v[64:67]
	s_setprio 0
	s_setprio 1
	v_mfma_f32_16x16x32_bf16 v[120:123], v[144:147], v[172:175], v[120:123]
	v_mfma_f32_16x16x32_bf16 v[116:119], v[164:167], v[172:175], v[116:119]
	v_mfma_f32_16x16x32_bf16 v[104:107], v[144:147], v[186:189], v[104:107]
	v_mfma_f32_16x16x32_bf16 v[100:103], v[164:167], v[186:189], v[100:103]
	v_mfma_f32_16x16x32_bf16 v[88:91], v[144:147], v[198:201], v[88:91]
	v_mfma_f32_16x16x32_bf16 v[84:87], v[164:167], v[198:201], v[84:87]
	v_mfma_f32_16x16x32_bf16 v[72:75], v[144:147], v[224:227], v[72:75]
	v_mfma_f32_16x16x32_bf16 v[68:71], v[164:167], v[224:227], v[68:71]
	v_mfma_f32_16x16x32_bf16 v[120:123], v[148:151], v[176:179], v[120:123]
	v_mfma_f32_16x16x32_bf16 v[116:119], v[168:171], v[176:179], v[116:119]
	v_mfma_f32_16x16x32_bf16 v[104:107], v[148:151], v[194:197], v[104:107]
	v_mfma_f32_16x16x32_bf16 v[100:103], v[168:171], v[194:197], v[100:103]
	v_mfma_f32_16x16x32_bf16 v[88:91], v[148:151], v[216:219], v[88:91]
	v_mfma_f32_16x16x32_bf16 v[84:87], v[168:171], v[216:219], v[84:87]
	v_mfma_f32_16x16x32_bf16 v[72:75], v[148:151], v[230:233], v[72:75]
	v_mfma_f32_16x16x32_bf16 v[68:71], v[168:171], v[230:233], v[68:71]
	s_barrier
; #define PG8_STAGE(bufoff, gbase, voff) do { _Pragma("unroll") for (int _i = 0; _i < 2; ++_i) \
;         __builtin_amdgcn_global_load_lds((const unsigned*)((const char*)(gbase) + (voff)[_i]), (PG8_LAS unsigned*)(lds + (bufoff) + ldsw + _i * 8192), 16, 0, 0); } while (0)
; #define PG8_LDA(dst, b, h) do { _Pragma("unroll") for (int m = 0; m < 4; ++m) _Pragma("unroll") for (int k = 0; k < 2; ++k) dst[m][k] = *(const PG8_LAS bf16x8*)(lds + PG8_SA(b, h) + aoff + m * 2048 + k * 1024); } while (0)
; #define PG8_LDB(dst, b, h) do { _Pragma("unroll") for (int n = 0; n < 2; ++n) _Pragma("unroll") for (int k = 0; k < 2; ++k) dst[n][k] = *(const PG8_LAS bf16x8*)(lds + PG8_SB(b, h) + boff + n * 2048 + k * 1024); } while (0)
; #define PG8_MMA(ai, bj, At, Bt) do { __builtin_amdgcn_s_setprio(1); _Pragma("unroll") for (int m = 0; m < 4; ++m) _Pragma("unroll") for (int n = 0; n < 2; ++n) _Pragma("unroll") for (int k = 0; k < 2; ++k) \
;         acc[ai][bj][m][n] = __builtin_amdgcn_mfma_f32_16x16x32_bf16(Bt[n][k], At[m][k], acc[ai][bj][m][n], 0, 0, 0); __builtin_amdgcn_s_setprio(0); } while (0)
; #define PG8_WAIT_V(n) asm volatile("s_waitcnt vmcnt(" #n ")" ::: "memory")
; #define PG8_WAIT_L(n) asm volatile("s_waitcnt lgkmcnt(" #n ")" ::: "memory")
; #define PG8_BAR __builtin_amdgcn_s_barrier()
; #define PG8_SCHED __builtin_amdgcn_sched_barrier(0)
; template <class Epi, class Sched, bool ALIGN_EPI = false, bool SP2 = false>
; __device__ __forceinline__ void gemm_phase(PG8_LAS unsigned char* lds, const Gemm g, const Sched& S, const Epi& E) {
;     ...
;             PG8_LDB(B0, 1, 0); PG8_LDB(B1, 1, 1); PG8_SCHED; PG8_LDA(At, 1, 0); PG8_STAGE(PG8_SA(0, 1), a2 + hstep, voffA);
;             PG8_WAIT_V(8); PG8_WAIT_L(0); PG8_BAR; PG8_MMA(0, 0, At, B0); PG8_MMA(0, 1, At, B1); PG8_BAR; PG8_SCHED;
;             PG8_LDA(At, 1, 1); PG8_STAGE(PG8_SB(1, 0), b3, voffB); PG8_STAGE(PG8_SB(1, 1), b3 + hstep, voffB); PG8_STAGE(PG8_SA(1, 0), a3, voffA);
;             PG8_WAIT_V(8); PG8_WAIT_L(0); PG8_BAR; PG8_MMA(1, 0, At, B0); PG8_MMA(1, 1, At, B1); PG8_BAR; PG8_SCHED;
	s_setprio 0
	s_add_i32 s50, s63, s47
	v_lshl_add_u64 v[202:203], v[202:203], 0, s[70:71]
	s_mov_b32 m0, s50
	ds_read_b128 v[172:175], v193 offset:49152
	ds_read_b128 v[176:179], v193 offset:50176
	ds_read_b128 v[186:189], v193 offset:51200
	ds_read_b128 v[194:197], v193 offset:52224
	ds_read_b128 v[198:201], v193 offset:53248
	ds_read_b128 v[216:219], v193 offset:54272
	ds_read_b128 v[224:227], v193 offset:55296
	ds_read_b128 v[230:233], v193 offset:56320
	global_load_lds_dwordx4 v[202:203], off
	s_add_i32 m0, s50, 0x2000
	s_add_u32 s44, s44, 0x40080
	v_lshl_add_u64 v[202:203], v[208:209], 0, s[70:71]
	s_addc_u32 s45, s45, 0
	s_add_i32 s50, s73, s47
	global_load_lds_dwordx4 v[202:203], off
	v_lshl_add_u64 v[202:203], s[44:45], 0, v[180:181]
	s_mov_b32 m0, s50
	s_nop 0
	global_load_lds_dwordx4 v[202:203], off
	v_lshl_add_u64 v[202:203], s[44:45], 0, v[152:153]
	s_add_i32 m0, s50, 0x2000
	s_nop 0
	global_load_lds_dwordx4 v[202:203], off
	v_lshl_add_u64 v[202:203], v[220:221], 0, s[70:71]
	s_mov_b32 m0, s56
	s_nop 0
	global_load_lds_dwordx4 v[202:203], off
	v_lshl_add_u64 v[202:203], v[234:235], 0, s[70:71]
	s_mov_b32 m0, s57
	s_nop 0
	global_load_lds_dwordx4 v[202:203], off
	s_waitcnt vmcnt(8)
	s_waitcnt lgkmcnt(0)
	s_setprio 1
	s_barrier
	v_mfma_f32_16x16x32_bf16 v[60:63], v[128:131], v[172:175], v[60:63]
	v_mfma_f32_16x16x32_bf16 v[48:51], v[136:139], v[172:175], v[48:51]
	v_mfma_f32_16x16x32_bf16 v[44:47], v[128:131], v[186:189], v[44:47]
	v_mfma_f32_16x16x32_bf16 v[32:35], v[136:139], v[186:189], v[32:35]
	v_mfma_f32_16x16x32_bf16 v[28:31], v[128:131], v[198:201], v[28:31]
	v_mfma_f32_16x16x32_bf16 v[16:19], v[136:139], v[198:201], v[16:19]
	v_mfma_f32_16x16x32_bf16 v[12:15], v[128:131], v[224:227], v[12:15]
	v_mfma_f32_16x16x32_bf16 v[4:7], v[136:139], v[224:227], v[4:7]
	v_mfma_f32_16x16x32_bf16 v[60:63], v[132:135], v[176:179], v[60:63]
	v_mfma_f32_16x16x32_bf16 v[48:51], v[140:143], v[176:179], v[48:51]
	v_mfma_f32_16x16x32_bf16 v[44:47], v[132:135], v[194:197], v[44:47]
	v_mfma_f32_16x16x32_bf16 v[32:35], v[140:143], v[194:197], v[32:35]
	v_mfma_f32_16x16x32_bf16 v[28:31], v[132:135], v[216:219], v[28:31]
	v_mfma_f32_16x16x32_bf16 v[16:19], v[140:143], v[216:219], v[16:19]
	v_mfma_f32_16x16x32_bf16 v[12:15], v[132:135], v[230:233], v[12:15]
	v_mfma_f32_16x16x32_bf16 v[4:7], v[140:143], v[230:233], v[4:7]
	s_setprio 0
	s_setprio 1
	v_mfma_f32_16x16x32_bf16 v[56:59], v[144:147], v[172:175], v[56:59]
	v_mfma_f32_16x16x32_bf16 v[52:55], v[164:167], v[172:175], v[52:55]
	v_mfma_f32_16x16x32_bf16 v[40:43], v[144:147], v[186:189], v[40:43]
	v_mfma_f32_16x16x32_bf16 v[36:39], v[164:167], v[186:189], v[36:39]
	v_mfma_f32_16x16x32_bf16 v[24:27], v[144:147], v[198:201], v[24:27]
	v_mfma_f32_16x16x32_bf16 v[20:23], v[164:167], v[198:201], v[20:23]
	v_mfma_f32_16x16x32_bf16 v[8:11], v[144:147], v[224:227], v[8:11]
	v_mfma_f32_16x16x32_bf16 v[0:3], v[164:167], v[224:227], v[0:3]
	v_mfma_f32_16x16x32_bf16 v[56:59], v[148:151], v[176:179], v[56:59]
	v_mfma_f32_16x16x32_bf16 v[52:55], v[168:171], v[176:179], v[52:55]
	v_mfma_f32_16x16x32_bf16 v[40:43], v[148:151], v[194:197], v[40:43]
	v_mfma_f32_16x16x32_bf16 v[36:39], v[168:171], v[194:197], v[36:39]
	v_mfma_f32_16x16x32_bf16 v[24:27], v[148:151], v[216:219], v[24:27]
	v_mfma_f32_16x16x32_bf16 v[20:23], v[168:171], v[216:219], v[20:23]
	v_mfma_f32_16x16x32_bf16 v[8:11], v[148:151], v[230:233], v[8:11]
	v_mfma_f32_16x16x32_bf16 v[0:3], v[168:171], v[230:233], v[0:3]
	s_barrier
	s_setprio 0
	s_add_i32 s62, s62, 2
	s_add_u32 s6, s6, 0x100
	s_addc_u32 s7, s7, 0
	s_add_u32 s60, s60, 0x100
	s_addc_u32 s61, s61, 0
	s_cmp_gt_u32 s62, 13
